# P7: next iteration's two x1b rows loaded at the start of the router (software-pipelined into v202-217), consumed at the next loop top
# speedup vs baseline: 1.0266x; 1.0025x over previous
; DI float bf_lo(unsigned u) { return __uint_as_float(u << 16); }
; DI float bf_hi(unsigned u) { return __uint_as_float(u & 0xffff0000u); }
; DI void phase7(const Params& p, char* smem) {
;     ...
;       const bool up = lane & 32;
; #pragma unroll
;       for (int j = 0; j < 8; ++j) { const float send = up ? a[j] : a[j + 8]; const float keep = up ? a[j + 8] : a[j]; a8[j] = keep + __shfl_xor(send, 32); }
;     }
;     {
;       const bool up = lane & 16;
; #pragma unroll
;       for (int j = 0; j < 4; ++j) { const float send = up ? a8[j] : a8[j + 4]; const float keep = up ? a8[j + 4] : a8[j]; a4[j] = keep + __shfl_xor(send, 16); }
;     }
;     {
;       const bool up = lane & 8;
; #pragma unroll
;       for (int j = 0; j < 2; ++j) { const float send = up ? a4[j] : a4[j + 2]; const float keep = up ? a4[j + 2] : a4[j]; a2[j] = keep + __shfl_xor(send, 8); }
;     }
;     {
;       const bool up = lane & 4;
;       const float send = up ? a2[0] : a2[1]; const float keep = up ? a2[1] : a2[0]; a1 = keep + __shfl_xor(send, 4);
;     }
;     a1 += __shfl_xor(a1, 2);
;     a1 += __shfl_xor(a1, 1);
;     float mx = a1;
; #pragma unroll
;     for (int o = 4; o <= 32; o <<= 1) mx = fmaxf(mx, __shfl_xor(mx, o));
;     ...
;   for (int R0 = gw; R0 < NT; R0 += 2 * nw) {
;     const int R1 = R0 + nw;
;     const bool has1 = R1 < NT;
;     const bf16_t* src0 = p.x1b + (size_t)R0 * DM;
;     const bf16_t* src1 = p.x1b + (size_t)(has1 ? R1 : R0) * DM;
;     const float* md0 = p.mod + (R0 >> 11) * 6144;
;     const float* md1 = p.mod + ((has1 ? R1 : R0) >> 11) * 6144;
;     float4 v0[4], v1[4]; float s0 = 0.f, s1 = 0.f;
; #pragma unroll
;     for (int i = 0; i < 4; ++i) {
;       const uint2 u0 = *(const uint2*)(src0 + lane * 4 + 256 * i), u1 = *(const uint2*)(src1 + lane * 4 + 256 * i);
;       v0[i] = make_float4(bf_lo(u0.x), bf_hi(u0.x), bf_lo(u0.y), bf_hi(u0.y)); v1[i] = make_float4(bf_lo(u1.x), bf_hi(u1.x), bf_lo(u1.y), bf_hi(u1.y));
.LBB0_952:
	s_or_b64 exec, exec, s[4:5]
	s_load_dwordx2 s[84:85], s[0:1], 0xb8
	v_ashrrev_i32_e32 v1, 6, v0
	v_readlane_b32 s4, v252, 2
	s_mov_b32 s35, 0x10000
	s_waitcnt lgkmcnt(0)
	v_add_u32_e32 v4, s4, v1
	v_cmp_gt_i32_e32 vcc, s35, v4
	s_barrier
	s_and_saveexec_b64 s[18:19], vcc
	s_cbranch_execz .LBB0_968
	v_lshlrev_b32_e32 v1, 2, v0
	v_and_b32_e32 v2, 0xfc, v1
	v_mbcnt_hi_u32_b32 v1, -1, v221
	v_and_b32_e32 v3, 64, v1
	v_add_u32_e32 v3, 64, v3
	v_xor_b32_e32 v5, 32, v1
	v_cmp_lt_i32_e32 vcc, v5, v3
	s_load_dwordx2 s[14:15], s[0:1], 0x120
	s_load_dwordx2 s[20:21], s[0:1], 0x130
	v_cndmask_b32_e32 v5, v1, v5, vcc
	v_lshlrev_b32_e32 v11, 2, v5
	v_xor_b32_e32 v5, 16, v1
	v_cmp_lt_i32_e32 vcc, v5, v3
	v_bfe_u32 v85, v0, 2, 4
	s_load_dwordx2 s[26:27], s[0:1], 0x160
	s_load_dwordx2 s[98:99], s[0:1], 0x160
	v_cndmask_b32_e32 v5, v1, v5, vcc
	v_lshlrev_b32_e32 v13, 2, v5
	v_xor_b32_e32 v5, 8, v1
	v_cmp_lt_i32_e32 vcc, v5, v3
	s_lshl_b32 s22, s3, 4
	v_mov_b32_e32 v7, 0
	v_cndmask_b32_e32 v5, v1, v5, vcc
	v_lshlrev_b32_e32 v15, 2, v5
	v_xor_b32_e32 v5, 4, v1
	v_cmp_lt_i32_e32 vcc, v5, v3
	v_lshlrev_b32_e32 v8, 2, v2
	v_lshlrev_b32_e32 v6, 1, v2
	v_cndmask_b32_e32 v5, v1, v5, vcc
	v_lshlrev_b32_e32 v31, 2, v5
	v_xor_b32_e32 v5, 2, v1
	v_cmp_lt_i32_e32 vcc, v5, v3
	v_mov_b32_e32 v9, v7
	s_ashr_i32 s23, s22, 31
	v_cndmask_b32_e32 v5, v1, v5, vcc
	v_lshlrev_b32_e32 v77, 2, v5
	v_xor_b32_e32 v5, 1, v1
	v_cmp_lt_i32_e32 vcc, v5, v3
	v_or_b32_e32 v10, 0x100, v2
	v_or_b32_e32 v12, 0x200, v2
	v_cndmask_b32_e32 v1, v1, v5, vcc
	v_lshlrev_b32_e32 v84, 2, v1
	v_and_b32_e32 v1, 32, v0
	v_cmp_eq_u32_e64 s[4:5], 0, v1
	v_and_b32_e32 v1, 16, v0
	v_cmp_eq_u32_e64 s[6:7], 0, v1
	v_and_b32_e32 v1, 8, v0
	v_cmp_eq_u32_e64 s[8:9], 0, v1
	v_and_b32_e32 v1, 4, v0
	v_cmp_eq_u32_e64 s[10:11], 0, v1
	v_and_b32_e32 v1, 3, v0
	v_and_b32_e32 v0, 63, v0
	v_lshlrev_b32_e32 v20, 3, v0
	v_add_u32_e32 v0, s33, v4
	v_cmp_eq_u32_e64 s[12:13], 0, v1
	v_ashrrev_i32_e32 v1, 31, v0
	v_lshlrev_b64 v[0:1], 11, v[0:1]
	v_ashrrev_i32_e32 v5, 31, v4
	s_waitcnt lgkmcnt(0)
	v_lshl_add_u64 v[22:23], s[14:15], 0, v[0:1]
	v_lshlrev_b64 v[0:1], 11, v[4:5]
	v_or_b32_e32 v14, 0x300, v2
	v_lshl_add_u64 v[16:17], s[26:27], 0, v[6:7]
	v_lshl_add_u64 v[18:19], s[16:17], 0, v[8:9]
	v_mov_b32_e32 v21, v7
	s_lshl_b64 s[24:25], s[22:23], 11
	v_lshl_add_u64 v[24:25], s[26:27], 0, v[0:1]
	v_lshl_add_u64 v[26:27], s[14:15], 0, v[0:1]
	s_mov_b64 s[26:27], 0
	s_mov_b64 s[28:29], 0x3000
	s_mov_b64 s[30:31], 0x4000
	v_lshlrev_b32_e32 v28, 2, v2
	v_mov_b32_e32 v29, v7
	s_mov_b32 s34, 0x3a800000
	v_mov_b32_e32 v30, 0x358637bd
	s_mov_b32 s23, 0x800000
	s_mov_b32 s36, 0xffff
	v_add_u32_e32 v219, s33, v4
	v_cmp_gt_i32_e64 s[38:39], s35, v219
	v_cndmask_b32_e64 v219, v4, v219, s[38:39]
	v_lshl_add_u32 v218, v4, 11, v20
	v_lshl_add_u32 v219, v219, 11, v20
	global_load_dwordx2 v[202:203], v218, s[98:99]
	global_load_dwordx2 v[204:205], v218, s[98:99] offset:512
	global_load_dwordx2 v[206:207], v218, s[98:99] offset:1024
	global_load_dwordx2 v[208:209], v218, s[98:99] offset:1536
	global_load_dwordx2 v[210:211], v219, s[98:99]
	global_load_dwordx2 v[212:213], v219, s[98:99] offset:512
	global_load_dwordx2 v[214:215], v219, s[98:99] offset:1024
	global_load_dwordx2 v[216:217], v219, s[98:99] offset:1536
	s_waitcnt vmcnt(0)
	s_branch .LBB0_955

; DI unsigned pk_bf16(float lo, float hi) { f32x2v v = {lo, hi}; bf16x2v b = __builtin_convertvector(v, bf16x2v); return __builtin_bit_cast(unsigned, b); }
; DI float bf_lo(unsigned u) { return __uint_as_float(u << 16); }
; DI float bf_hi(unsigned u) { return __uint_as_float(u & 0xffff0000u); }
; DI void phase7(const Params& p, char* smem) {
;     ...
;   for (int R0 = gw; R0 < NT; R0 += 2 * nw) {
;     const int R1 = R0 + nw;
;     const bool has1 = R1 < NT;
;     const bf16_t* src0 = p.x1b + (size_t)R0 * DM;
;     const bf16_t* src1 = p.x1b + (size_t)(has1 ? R1 : R0) * DM;
;     const float* md0 = p.mod + (R0 >> 11) * 6144;
;     const float* md1 = p.mod + ((has1 ? R1 : R0) >> 11) * 6144;
;     float4 v0[4], v1[4]; float s0 = 0.f, s1 = 0.f;
; #pragma unroll
;     for (int i = 0; i < 4; ++i) {
;       const uint2 u0 = *(const uint2*)(src0 + lane * 4 + 256 * i), u1 = *(const uint2*)(src1 + lane * 4 + 256 * i);
;       v0[i] = make_float4(bf_lo(u0.x), bf_hi(u0.x), bf_lo(u0.y), bf_hi(u0.y)); v1[i] = make_float4(bf_lo(u1.x), bf_hi(u1.x), bf_lo(u1.y), bf_hi(u1.y));
;     }
; #pragma unroll
;     for (int i = 0; i < 4; ++i) { s0 += v0[i].x * v0[i].x + v0[i].y * v0[i].y + v0[i].z * v0[i].z + v0[i].w * v0[i].w; s1 += v1[i].x * v1[i].x + v1[i].y * v1[i].y + v1[i].z * v1[i].z + v1[i].w * v1[i].w; }
;     s0 = wave_sum(s0); s1 = wave_sum(s1);
;     const float r0 = rsqrtf(s0 * (1.f / DM) + EPS), r1 = rsqrtf(s1 * (1.f / DM) + EPS);
; #pragma unroll
;     for (int i = 0; i < 4; ++i) {
;       const int d = lane * 4 + 256 * i;
;       const float4 g = *(const float4*)(p.norm2_g + d);
;       {
;         const float4 sh = *(const float4*)(md0 + 3072 + d), sc = *(const float4*)(md0 + 4096 + d);
;         v0[i].x = v0[i].x * r0 * g.x * (1.f + sc.x) + sh.x; v0[i].y = v0[i].y * r0 * g.y * (1.f + sc.y) + sh.y;
;         v0[i].z = v0[i].z * r0 * g.z * (1.f + sc.z) + sh.z; v0[i].w = v0[i].w * r0 * g.w * (1.f + sc.w) + sh.w;
;         uint2 o; o.x = pk_bf16(v0[i].x, v0[i].y); o.y = pk_bf16(v0[i].z, v0[i].w);
;         *(uint2*)(p.h2 + (size_t)R0 * DM + d) = o;
;       }
.LBB0_955:
	v_add_u32_e32 v5, s33, v4
	v_cmp_gt_i32_e64 s[14:15], s35, v5
	v_cndmask_b32_e64 v70, v4, v5, s[14:15]
	v_ashrrev_i32_e32 v71, 31, v70
	v_ashrrev_i32_e32 v6, 11, v4
	v_mul_i32_i24_e32 v42, 0x1800, v6
	v_ashrrev_i32_e32 v43, 31, v42
	v_lshl_add_u64 v[42:43], v[42:43], 2, s[84:85]
	v_lshl_add_u64 v[60:61], v[42:43], 0, s[28:29]
	v_lshl_add_u64 v[62:63], v[42:43], 0, s[30:31]
	v_lshl_add_u64 v[42:43], v[60:61], 0, v[28:29]
	s_waitcnt lgkmcnt(0)
	global_load_dwordx4 v[0:3], v[18:19], off
	v_lshl_add_u64 v[44:45], v[62:63], 0, v[28:29]
	global_load_dwordx4 v[48:51], v[42:43], off
	global_load_dwordx4 v[78:81], v[44:45], off
	v_ashrrev_i32_e32 v6, 11, v70
	v_mul_i32_i24_e32 v70, 0x1800, v6
	v_ashrrev_i32_e32 v71, 31, v70
	v_lshl_add_u64 v[190:191], v[70:71], 2, s[84:85]
	v_lshl_add_u64 v[192:193], v[190:191], 0, s[28:29]
	v_lshl_add_u64 v[190:191], v[190:191], 0, s[30:31]
	v_lshl_add_u64 v[192:193], v[192:193], 0, v[28:29]
	v_lshl_add_u64 v[190:191], v[190:191], 0, v[28:29]
	global_load_dwordx4 v[158:161], v[190:191], off
	global_load_dwordx4 v[174:177], v[192:193], off
	global_load_dwordx4 v[114:117], v[18:19], off offset:1024
	global_load_dwordx4 v[130:133], v[44:45], off offset:1024
	global_load_dwordx4 v[146:149], v[42:43], off offset:1024
	global_load_dwordx4 v[162:165], v[190:191], off offset:1024
	global_load_dwordx4 v[178:181], v[192:193], off offset:1024
	global_load_dwordx4 v[118:121], v[18:19], off offset:2048
	global_load_dwordx4 v[134:137], v[44:45], off offset:2048
	global_load_dwordx4 v[150:153], v[42:43], off offset:2048
	global_load_dwordx4 v[166:169], v[190:191], off offset:2048
	global_load_dwordx4 v[182:185], v[192:193], off offset:2048
	global_load_dwordx4 v[122:125], v[18:19], off offset:3072
	global_load_dwordx4 v[138:141], v[44:45], off offset:3072
	global_load_dwordx4 v[154:157], v[42:43], off offset:3072
	global_load_dwordx4 v[170:173], v[190:191], off offset:3072
	global_load_dwordx4 v[186:189], v[192:193], off offset:3072
	v_lshlrev_b32_e32 v88, 16, v202
	v_and_b32_e32 v89, 0xffff0000, v202
	v_and_b32_e32 v68, 0xffff0000, v206
	v_and_b32_e32 v67, 0xffff0000, v208
	v_lshlrev_b32_e32 v66, 16, v208
	v_mov_b32_e32 v69, v67
	v_lshlrev_b32_e32 v90, 16, v203
	v_and_b32_e32 v91, 0xffff0000, v203
	v_lshlrev_b32_e32 v58, 16, v206
	v_lshlrev_b32_e32 v56, 16, v207
	v_and_b32_e32 v72, 0xffff0000, v207
	v_mov_b32_e32 v59, v66
	v_pk_mul_f32 v[32:33], v[68:69], v[68:69]
	v_lshlrev_b32_e32 v42, 16, v211
	v_and_b32_e32 v43, 0xffff0000, v211
	v_and_b32_e32 v41, 0xffff0000, v214
	v_and_b32_e32 v37, 0xffff0000, v216
	v_lshlrev_b32_e32 v64, 16, v209
	v_pk_fma_f32 v[94:95], v[58:59], v[58:59], v[32:33]
	v_lshlrev_b32_e32 v46, 16, v210
	v_and_b32_e32 v47, 0xffff0000, v210
	v_and_b32_e32 v45, 0xffff0000, v212
	v_lshlrev_b32_e32 v40, 16, v214
	v_lshlrev_b32_e32 v36, 16, v216
	v_lshlrev_b32_e32 v32, 16, v217
	v_and_b32_e32 v33, 0xffff0000, v217
	v_mov_b32_e32 v86, v41
	v_mov_b32_e32 v87, v37
	v_lshlrev_b32_e32 v54, 16, v204
	v_and_b32_e32 v55, 0xffff0000, v204
	v_lshlrev_b32_e32 v52, 16, v205
	v_and_b32_e32 v53, 0xffff0000, v205
	v_mov_b32_e32 v57, v64
	v_lshlrev_b32_e32 v44, 16, v212
	v_lshlrev_b32_e32 v34, 16, v215
	v_and_b32_e32 v35, 0xffff0000, v215
	v_mov_b32_e32 v82, v40
	v_mov_b32_e32 v83, v36
	v_mov_b32_e32 v100, v47
	v_mov_b32_e32 v101, v45
	v_pk_mul_f32 v[86:87], v[86:87], v[86:87]
	v_and_b32_e32 v65, 0xffff0000, v209
	v_lshlrev_b32_e32 v38, 16, v213
	v_and_b32_e32 v39, 0xffff0000, v213
	v_pk_fma_f32 v[74:75], v[56:57], v[56:57], v[94:95]
	v_mov_b32_e32 v94, v34
	v_mov_b32_e32 v95, v32
	v_mov_b32_e32 v98, v46
	v_mov_b32_e32 v99, v44
	v_pk_mul_f32 v[100:101], v[100:101], v[100:101]
	v_pk_fma_f32 v[82:83], v[82:83], v[82:83], v[86:87]
	v_mov_b32_e32 v96, v35
	v_mov_b32_e32 v97, v33
	v_pk_fma_f32 v[86:87], v[98:99], v[98:99], v[100:101]
	v_pk_fma_f32 v[82:83], v[94:95], v[94:95], v[82:83]
	v_mov_b32_e32 v98, v89
	v_mov_b32_e32 v99, v55
	v_pk_fma_f32 v[82:83], v[96:97], v[96:97], v[82:83]
	v_mov_b32_e32 v96, v88
	v_mov_b32_e32 v97, v54
	v_pk_mul_f32 v[98:99], v[98:99], v[98:99]
	v_mov_b32_e32 v92, v90
	v_mov_b32_e32 v102, v42
	v_mov_b32_e32 v103, v38
	v_mov_b32_e32 v93, v52
	v_pk_fma_f32 v[96:97], v[96:97], v[96:97], v[98:99]
	v_mov_b32_e32 v104, v43
	v_mov_b32_e32 v105, v39
	v_pk_fma_f32 v[86:87], v[102:103], v[102:103], v[86:87]
	v_mov_b32_e32 v94, v91
	v_mov_b32_e32 v95, v53
	v_pk_fma_f32 v[92:93], v[92:93], v[92:93], v[96:97]
	v_mov_b32_e32 v73, v65
	v_pk_fma_f32 v[86:87], v[104:105], v[104:105], v[86:87]
	v_pk_fma_f32 v[92:93], v[94:95], v[94:95], v[92:93]
	v_pk_fma_f32 v[74:75], v[72:73], v[72:73], v[74:75]
	v_mov_b32_e32 v94, v86
	v_mov_b32_e32 v95, v92
	v_mov_b32_e32 v92, v87
	v_pk_add_f32 v[86:87], v[94:95], v[92:93]
	v_mov_b32_e32 v92, v82
	v_mov_b32_e32 v93, v74
	v_pk_add_f32 v[86:87], v[86:87], v[92:93]
	v_mov_b32_e32 v74, v83
	v_pk_add_f32 v[74:75], v[86:87], v[74:75]
	ds_bpermute_b32 v82, v11, v74
	ds_bpermute_b32 v83, v11, v75
	s_waitcnt vmcnt(17)
	v_pk_add_f32 v[78:79], v[78:79], 1.0 op_sel_hi:[1,0]
	v_pk_add_f32 v[80:81], v[80:81], 1.0 op_sel_hi:[1,0]
	s_waitcnt lgkmcnt(0)
	v_pk_add_f32 v[74:75], v[74:75], v[82:83]
	ds_bpermute_b32 v82, v13, v74
	ds_bpermute_b32 v83, v13, v75
	s_waitcnt lgkmcnt(0)
	v_pk_add_f32 v[74:75], v[74:75], v[82:83]
	ds_bpermute_b32 v82, v15, v74
	ds_bpermute_b32 v83, v15, v75
	s_waitcnt lgkmcnt(0)
	v_pk_add_f32 v[74:75], v[74:75], v[82:83]
	ds_bpermute_b32 v82, v31, v74
	ds_bpermute_b32 v83, v31, v75
	s_waitcnt lgkmcnt(0)
	v_pk_add_f32 v[74:75], v[74:75], v[82:83]
	ds_bpermute_b32 v82, v77, v74
	ds_bpermute_b32 v83, v77, v75
	s_waitcnt lgkmcnt(0)
	v_pk_add_f32 v[82:83], v[74:75], v[82:83]
	ds_bpermute_b32 v86, v84, v82
	ds_bpermute_b32 v87, v84, v83
	v_lshl_add_u64 v[74:75], v[70:71], 2, s[84:85]
	v_lshl_add_u64 v[70:71], v[74:75], 0, s[28:29]
	v_lshl_add_u64 v[74:75], v[74:75], 0, s[30:31]
	s_waitcnt lgkmcnt(0)
	v_pk_add_f32 v[82:83], v[82:83], v[86:87]
	s_nop 0
	v_pk_fma_f32 v[82:83], v[82:83], s[34:35], v[30:31] op_sel_hi:[1,0,0]
	s_nop 0
	v_mul_f32_e32 v6, 0x4b800000, v82
	v_cmp_gt_f32_e32 vcc, s23, v82
	v_mul_f32_e32 v9, 0x4b800000, v83
	v_cmp_gt_f32_e64 s[16:17], s23, v83
	v_cndmask_b32_e32 v6, v82, v6, vcc
	v_rsq_f32_e32 v6, v6
	v_cndmask_b32_e64 v9, v83, v9, s[16:17]
	v_rsq_f32_e32 v9, v9
	v_mul_f32_e32 v57, 0x45800000, v6
	v_cndmask_b32_e32 v76, v6, v57, vcc
	v_mul_f32_e32 v6, 0x45800000, v9
	v_cndmask_b32_e64 v82, v9, v6, s[16:17]
	v_pk_mul_f32 v[86:87], v[82:83], v[88:89] op_sel_hi:[0,1]
	v_pk_mul_f32 v[86:87], v[0:1], v[86:87]
	s_nop 0
	v_pk_fma_f32 v[48:49], v[86:87], v[78:79], v[48:49]
	v_pk_mul_f32 v[78:79], v[82:83], v[90:91] op_sel_hi:[0,1]
	v_pk_mul_f32 v[78:79], v[2:3], v[78:79]
	s_nop 0
	v_pk_fma_f32 v[50:51], v[78:79], v[80:81], v[50:51]
	v_cvt_pk_bf16_f32 v78, v48, v49
	v_cvt_pk_bf16_f32 v79, v50, v51
	v_lshl_add_u64 v[80:81], v[26:27], 0, v[20:21]
	global_store_dwordx2 v[80:81], v[78:79], off
	v_lshl_add_u64 v[78:79], v[22:23], 0, v[20:21]
	s_and_saveexec_b64 s[16:17], s[14:15]
	s_cbranch_execz .LBB0_957
; DI unsigned pk_bf16(float lo, float hi) { f32x2v v = {lo, hi}; bf16x2v b = __builtin_convertvector(v, bf16x2v); return __builtin_bit_cast(unsigned, b); }
; DI void phase7(const Params& p, char* smem) {
;     ...
;       if (has1) {
;         const float4 sh = *(const float4*)(md1 + 3072 + d), sc = *(const float4*)(md1 + 4096 + d);
;         v1[i].x = v1[i].x * r1 * g.x * (1.f + sc.x) + sh.x; v1[i].y = v1[i].y * r1 * g.y * (1.f + sc.y) + sh.y;
;         v1[i].z = v1[i].z * r1 * g.z * (1.f + sc.z) + sh.z; v1[i].w = v1[i].w * r1 * g.w * (1.f + sc.w) + sh.w;
;         uint2 o; o.x = pk_bf16(v1[i].x, v1[i].y); o.y = pk_bf16(v1[i].z, v1[i].w);
;         *(uint2*)(p.h2 + (size_t)R1 * DM + d) = o;
;       }
	s_waitcnt vmcnt(16)
	v_pk_mul_f32 v[46:47], v[76:77], v[46:47] op_sel_hi:[0,1]
	v_pk_mul_f32 v[42:43], v[76:77], v[42:43] op_sel_hi:[0,1]
	v_pk_mul_f32 v[0:1], v[0:1], v[46:47]
	v_pk_mul_f32 v[2:3], v[2:3], v[42:43]
	v_pk_add_f32 v[42:43], v[158:159], 1.0 op_sel_hi:[1,0]
	v_pk_add_f32 v[158:159], v[160:161], 1.0 op_sel_hi:[1,0]
	v_pk_fma_f32 v[46:47], v[0:1], v[42:43], v[174:175]
	v_pk_fma_f32 v[42:43], v[2:3], v[158:159], v[176:177]
	v_cvt_pk_bf16_f32 v0, v46, v47
	v_cvt_pk_bf16_f32 v1, v42, v43
	global_store_dwordx2 v[78:79], v[0:1], off

; DI void phase7(const Params& p, char* smem) {
;     ...
;   auto router = [&](const float4 (&v)[4], int R) {
;     asm volatile("" ::: "memory");
;     float a[16];
; #pragma unroll
;     for (int e = 0; e < 16; ++e) {
;       float s = 0.f;
; #pragma unroll
;       for (int i = 0; i < 4; ++i) { const float4 wv = *(const float4*)(wr + e * DM + lane * 4 + 256 * i); s += v[i].x * wv.x + v[i].y * wv.y + v[i].z * wv.z + v[i].w * wv.w; }
;       a[e] = s;
;       if ((e & 3) == 3) __builtin_amdgcn_sched_barrier(0);
;     }
;     ...
;   for (int R0 = gw; R0 < NT; R0 += 2 * nw) {
;     const int R1 = R0 + nw;
;     const bool has1 = R1 < NT;
;     const bf16_t* src0 = p.x1b + (size_t)R0 * DM;
;     const bf16_t* src1 = p.x1b + (size_t)(has1 ? R1 : R0) * DM;
;     const float* md0 = p.mod + (R0 >> 11) * 6144;
;     const float* md1 = p.mod + ((has1 ? R1 : R0) >> 11) * 6144;
.LBB0_963:
	s_or_b64 exec, exec, s[16:17]
	v_add_u32_e32 v218, s22, v4
	v_cmp_gt_i32_e64 s[38:39], s35, v218
	v_cndmask_b32_e64 v218, v4, v218, s[38:39]
	v_add_u32_e32 v219, s33, v218
	v_cmp_gt_i32_e64 s[38:39], s35, v219
	v_cndmask_b32_e64 v219, v218, v219, s[38:39]
	v_lshl_add_u32 v218, v218, 11, v20
	v_lshl_add_u32 v219, v219, 11, v20
	global_load_dwordx2 v[202:203], v218, s[98:99]
	global_load_dwordx2 v[204:205], v218, s[98:99] offset:512
	global_load_dwordx2 v[206:207], v218, s[98:99] offset:1024
	global_load_dwordx2 v[208:209], v218, s[98:99] offset:1536
	global_load_dwordx2 v[210:211], v219, s[98:99]
	global_load_dwordx2 v[212:213], v219, s[98:99] offset:512
	global_load_dwordx2 v[214:215], v219, s[98:99] offset:1024
	global_load_dwordx2 v[216:217], v219, s[98:99] offset:1536
	ds_read_b128 v[0:3], v8
	ds_read_b128 v[64:67], v8 offset:1024
	ds_read_b128 v[68:71], v8 offset:2048
	s_waitcnt lgkmcnt(2)
	v_mul_f32_e32 v111, v47, v1
	v_mul_f32_e32 v1, v49, v1
	s_waitcnt lgkmcnt(1)
	v_mul_f32_e32 v116, v45, v65
	v_mul_f32_e32 v6, v55, v65
	v_fmac_f32_e32 v111, v46, v0
	v_fmac_f32_e32 v1, v48, v0
	v_fmac_f32_e32 v116, v44, v64
	v_fmac_f32_e32 v6, v54, v64
	v_fmac_f32_e32 v111, v42, v2
	v_fmac_f32_e32 v1, v50, v2
	v_fmac_f32_e32 v111, v43, v3
	v_fmac_f32_e32 v1, v51, v3
	v_fmac_f32_e32 v116, v38, v66
	v_fmac_f32_e32 v6, v52, v66
	v_add_f32_e32 v110, 0, v111
	v_add_f32_e32 v0, 0, v1
	v_fmac_f32_e32 v116, v39, v67
	v_fmac_f32_e32 v6, v53, v67
	v_add_f32_e32 v116, v110, v116
	v_add_f32_e32 v6, v0, v6
	ds_read_b128 v[0:3], v8 offset:3072
	ds_read_b128 v[64:67], v8 offset:4096
	s_waitcnt lgkmcnt(2)
	v_mul_f32_e32 v119, v41, v69
	v_mul_f32_e32 v9, v59, v69
	v_fmac_f32_e32 v119, v40, v68
	v_fmac_f32_e32 v9, v58, v68
	v_fmac_f32_e32 v119, v34, v70
	v_fmac_f32_e32 v9, v56, v70
	s_waitcnt lgkmcnt(1)
	v_mul_f32_e32 v111, v37, v1
	v_mul_f32_e32 v1, v63, v1
	v_fmac_f32_e32 v111, v36, v0
	v_fmac_f32_e32 v1, v62, v0
	v_fmac_f32_e32 v119, v35, v71
	v_fmac_f32_e32 v9, v57, v71
	v_fmac_f32_e32 v111, v32, v2
	v_fmac_f32_e32 v1, v60, v2
	v_add_f32_e32 v116, v116, v119
	v_add_f32_e32 v6, v6, v9
	v_fmac_f32_e32 v111, v33, v3
	v_fmac_f32_e32 v1, v61, v3
	ds_read_b128 v[68:71], v8 offset:5120
	v_add_f32_e32 v110, v116, v111
	v_add_f32_e32 v0, v6, v1
	s_waitcnt lgkmcnt(1)
	v_mul_f32_e32 v111, v47, v65
	v_mul_f32_e32 v1, v49, v65
	v_fmac_f32_e32 v111, v46, v64
	v_fmac_f32_e32 v1, v48, v64
	v_fmac_f32_e32 v111, v42, v66
	v_fmac_f32_e32 v1, v50, v66
	v_fmac_f32_e32 v111, v43, v67
	v_fmac_f32_e32 v1, v51, v67
	ds_read_b128 v[64:67], v8 offset:6144
	s_waitcnt lgkmcnt(1)
	v_mul_f32_e32 v112, v45, v69
	v_mul_f32_e32 v2, v55, v69
	v_fmac_f32_e32 v112, v44, v68
	v_fmac_f32_e32 v2, v54, v68
	v_fmac_f32_e32 v112, v38, v70
	v_fmac_f32_e32 v2, v52, v70
	v_add_f32_e32 v111, 0, v111
	v_add_f32_e32 v1, 0, v1
	v_fmac_f32_e32 v112, v39, v71
	v_fmac_f32_e32 v2, v53, v71
	ds_read_b128 v[68:71], v8 offset:7168
	v_add_f32_e32 v111, v111, v112
	v_add_f32_e32 v1, v1, v2
	s_waitcnt lgkmcnt(1)
	v_mul_f32_e32 v112, v41, v65
	v_mul_f32_e32 v2, v59, v65
	v_fmac_f32_e32 v112, v40, v64
	v_fmac_f32_e32 v2, v58, v64
	v_fmac_f32_e32 v112, v34, v66
	v_fmac_f32_e32 v2, v56, v66
	v_fmac_f32_e32 v112, v35, v67
	v_fmac_f32_e32 v2, v57, v67
	ds_read_b128 v[64:67], v8 offset:9216
	ds_read_b128 v[72:75], v8 offset:8192
	v_add_f32_e32 v111, v111, v112
	v_add_f32_e32 v1, v1, v2
	s_waitcnt lgkmcnt(2)
	v_mul_f32_e32 v112, v37, v69
	v_mul_f32_e32 v2, v63, v69
	v_fmac_f32_e32 v112, v36, v68
	v_fmac_f32_e32 v2, v62, v68
	v_fmac_f32_e32 v112, v32, v70
	v_fmac_f32_e32 v2, v60, v70
	v_fmac_f32_e32 v112, v33, v71
	v_fmac_f32_e32 v2, v61, v71
	v_add_f32_e32 v111, v111, v112
	v_add_f32_e32 v1, v1, v2
	ds_read_b128 v[68:71], v8 offset:11264
	ds_read_b128 v[78:81], v8 offset:10240
	s_waitcnt lgkmcnt(2)
	v_mul_f32_e32 v112, v46, v72
	v_mul_f32_e32 v2, v48, v72
	v_fmac_f32_e32 v112, v47, v73
	v_fmac_f32_e32 v2, v49, v73
	v_mul_f32_e32 v113, v44, v64
	v_mul_f32_e32 v3, v54, v64
	v_fmac_f32_e32 v112, v42, v74
	v_fmac_f32_e32 v2, v50, v74
	v_fmac_f32_e32 v113, v45, v65
	v_fmac_f32_e32 v3, v55, v65
	v_fmac_f32_e32 v112, v43, v75
	v_fmac_f32_e32 v2, v51, v75
	v_fmac_f32_e32 v113, v38, v66
	v_fmac_f32_e32 v3, v52, v66
	v_add_f32_e32 v112, 0, v112
	v_add_f32_e32 v2, 0, v2
	v_fmac_f32_e32 v113, v39, v67
	v_fmac_f32_e32 v3, v53, v67
	v_add_f32_e32 v112, v113, v112
	v_add_f32_e32 v2, v3, v2
	s_waitcnt lgkmcnt(0)
	v_mul_f32_e32 v113, v40, v78
	v_mul_f32_e32 v3, v58, v78
	v_fmac_f32_e32 v113, v41, v79
	v_fmac_f32_e32 v3, v59, v79
	v_fmac_f32_e32 v113, v34, v80
	v_fmac_f32_e32 v3, v56, v80
	v_fmac_f32_e32 v113, v35, v81
	v_fmac_f32_e32 v3, v57, v81
	ds_read_b128 v[64:67], v8 offset:13312
	ds_read_b128 v[72:75], v8 offset:12288
	v_add_f32_e32 v112, v113, v112
	v_add_f32_e32 v2, v3, v2
	v_mul_f32_e32 v113, v36, v68
	v_mul_f32_e32 v3, v62, v68
	v_fmac_f32_e32 v113, v37, v69
	v_fmac_f32_e32 v3, v63, v69
	v_fmac_f32_e32 v113, v32, v70
	v_fmac_f32_e32 v3, v60, v70
	v_fmac_f32_e32 v113, v33, v71
	v_fmac_f32_e32 v3, v61, v71
	v_add_f32_e32 v112, v113, v112
	v_add_f32_e32 v2, v3, v2
	ds_read_b128 v[68:71], v8 offset:15360
	ds_read_b128 v[78:81], v8 offset:14336
	s_waitcnt lgkmcnt(2)
	v_mul_f32_e32 v113, v46, v72
	v_mul_f32_e32 v3, v48, v72
	v_fmac_f32_e32 v113, v47, v73
	v_fmac_f32_e32 v3, v49, v73
	v_mul_f32_e32 v116, v44, v64
	v_mul_f32_e32 v6, v54, v64
	v_fmac_f32_e32 v113, v42, v74
	v_fmac_f32_e32 v3, v50, v74
	v_fmac_f32_e32 v116, v45, v65
	v_fmac_f32_e32 v6, v55, v65
	v_fmac_f32_e32 v113, v43, v75
	v_fmac_f32_e32 v3, v51, v75
	v_fmac_f32_e32 v116, v38, v66
	v_fmac_f32_e32 v6, v52, v66
	v_add_f32_e32 v113, 0, v113
	v_add_f32_e32 v3, 0, v3
	v_fmac_f32_e32 v116, v39, v67
	v_fmac_f32_e32 v6, v53, v67
	v_add_f32_e32 v113, v116, v113
	v_add_f32_e32 v3, v6, v3
	s_waitcnt lgkmcnt(0)
; DI void phase7(const Params& p, char* smem) {
;     ...
; #pragma unroll
;     for (int e = 0; e < 16; ++e) {
;       float s = 0.f;
; #pragma unroll
;       for (int i = 0; i < 4; ++i) { const float4 wv = *(const float4*)(wr + e * DM + lane * 4 + 256 * i); s += v[i].x * wv.x + v[i].y * wv.y + v[i].z * wv.z + v[i].w * wv.w; }
;       a[e] = s;
;       if ((e & 3) == 3) __builtin_amdgcn_sched_barrier(0);
;     }
	v_mul_f32_e32 v116, v40, v78
	v_mul_f32_e32 v6, v58, v78
	v_fmac_f32_e32 v116, v41, v79
	v_fmac_f32_e32 v6, v59, v79
	v_fmac_f32_e32 v116, v34, v80
	v_fmac_f32_e32 v6, v56, v80
	v_fmac_f32_e32 v116, v35, v81
	v_fmac_f32_e32 v6, v57, v81
	v_add_f32_e32 v113, v116, v113
	v_add_f32_e32 v3, v6, v3
	v_mul_f32_e32 v116, v36, v68
	v_mul_f32_e32 v6, v62, v68
	v_fmac_f32_e32 v116, v37, v69
	v_fmac_f32_e32 v6, v63, v69
	v_fmac_f32_e32 v116, v32, v70
	v_fmac_f32_e32 v6, v60, v70
	v_fmac_f32_e32 v116, v33, v71
	v_fmac_f32_e32 v6, v61, v71
	v_add_f32_e32 v113, v116, v113
	v_add_f32_e32 v3, v6, v3
	ds_read_b128 v[64:67], v8 offset:16384
	ds_read_b128 v[68:71], v8 offset:17408
	ds_read_b128 v[72:75], v8 offset:18432
	s_waitcnt lgkmcnt(2)
	v_mul_f32_e32 v116, v47, v65
	v_mul_f32_e32 v6, v49, v65
	s_waitcnt lgkmcnt(1)
	v_mul_f32_e32 v119, v45, v69
	v_mul_f32_e32 v9, v55, v69
	v_fmac_f32_e32 v116, v46, v64
	v_fmac_f32_e32 v6, v48, v64
	v_fmac_f32_e32 v119, v44, v68
	v_fmac_f32_e32 v9, v54, v68
	v_fmac_f32_e32 v116, v42, v66
	v_fmac_f32_e32 v6, v50, v66
	v_fmac_f32_e32 v116, v43, v67
	v_fmac_f32_e32 v6, v51, v67
	v_fmac_f32_e32 v119, v38, v70
	v_fmac_f32_e32 v9, v52, v70
	v_add_f32_e32 v116, 0, v116
	v_add_f32_e32 v6, 0, v6
	v_fmac_f32_e32 v119, v39, v71
	v_fmac_f32_e32 v9, v53, v71
	ds_read_b128 v[64:67], v8 offset:19456
	v_add_f32_e32 v116, v116, v119
	v_add_f32_e32 v6, v6, v9
	s_waitcnt lgkmcnt(1)
	v_mul_f32_e32 v119, v41, v73
	v_mul_f32_e32 v9, v59, v73
	v_fmac_f32_e32 v119, v40, v72
	v_fmac_f32_e32 v9, v58, v72
	v_fmac_f32_e32 v119, v34, v74
	v_fmac_f32_e32 v9, v56, v74
	v_fmac_f32_e32 v119, v35, v75
	v_fmac_f32_e32 v9, v57, v75
	ds_read_b128 v[68:71], v8 offset:21504
	ds_read_b128 v[72:75], v8 offset:20480
	v_add_f32_e32 v116, v116, v119
	v_add_f32_e32 v6, v6, v9
	s_waitcnt lgkmcnt(2)
	v_mul_f32_e32 v119, v37, v65
	v_mul_f32_e32 v9, v63, v65
	v_fmac_f32_e32 v119, v36, v64
	v_fmac_f32_e32 v9, v62, v64
	v_fmac_f32_e32 v119, v32, v66
	v_fmac_f32_e32 v9, v60, v66
	v_fmac_f32_e32 v119, v33, v67
	v_fmac_f32_e32 v9, v61, v67
	v_add_f32_e32 v116, v116, v119
	v_add_f32_e32 v6, v6, v9
	ds_read_b128 v[64:67], v8 offset:23552
	ds_read_b128 v[78:81], v8 offset:22528
	s_waitcnt lgkmcnt(2)
	v_mul_f32_e32 v119, v46, v72
	v_mul_f32_e32 v9, v48, v72
	v_fmac_f32_e32 v119, v47, v73
	v_fmac_f32_e32 v9, v49, v73
	v_mul_f32_e32 v178, v44, v68
	v_mul_f32_e32 v68, v54, v68
	v_fmac_f32_e32 v119, v42, v74
	v_fmac_f32_e32 v9, v50, v74
	v_fmac_f32_e32 v178, v45, v69
	v_fmac_f32_e32 v68, v55, v69
	v_fmac_f32_e32 v119, v43, v75
	v_fmac_f32_e32 v9, v51, v75
	v_fmac_f32_e32 v178, v38, v70
	v_fmac_f32_e32 v68, v52, v70
	v_add_f32_e32 v119, 0, v119
	v_add_f32_e32 v9, 0, v9
	v_fmac_f32_e32 v178, v39, v71
	v_fmac_f32_e32 v68, v53, v71
	v_add_f32_e32 v119, v178, v119
	v_add_f32_e32 v9, v68, v9
	s_waitcnt lgkmcnt(0)
	v_mul_f32_e32 v178, v40, v78
	v_mul_f32_e32 v68, v58, v78
	v_fmac_f32_e32 v178, v41, v79
	v_fmac_f32_e32 v68, v59, v79
	v_fmac_f32_e32 v178, v34, v80
	v_fmac_f32_e32 v68, v56, v80
	v_mul_f32_e32 v174, v36, v64
	v_mul_f32_e32 v64, v62, v64
	v_fmac_f32_e32 v178, v35, v81
	v_fmac_f32_e32 v68, v57, v81
	v_fmac_f32_e32 v174, v37, v65
	v_fmac_f32_e32 v64, v63, v65
	v_add_f32_e32 v119, v178, v119
	v_add_f32_e32 v9, v68, v9
	v_fmac_f32_e32 v174, v32, v66
	v_fmac_f32_e32 v64, v60, v66
	ds_read_b128 v[68:71], v8 offset:25600
	ds_read_b128 v[72:75], v8 offset:24576
	v_fmac_f32_e32 v174, v33, v67
	v_fmac_f32_e32 v64, v61, v67
	v_add_f32_e32 v119, v174, v119
	v_add_f32_e32 v9, v64, v9
	ds_read_b128 v[64:67], v8 offset:27648
	ds_read_b128 v[78:81], v8 offset:26624
	s_waitcnt lgkmcnt(3)
	v_mul_f32_e32 v178, v44, v68
	v_mul_f32_e32 v68, v54, v68
	s_waitcnt lgkmcnt(2)
	v_mul_f32_e32 v182, v46, v72
	v_mul_f32_e32 v72, v48, v72
	v_fmac_f32_e32 v182, v47, v73
	v_fmac_f32_e32 v72, v49, v73
	v_fmac_f32_e32 v182, v42, v74
	v_fmac_f32_e32 v72, v50, v74
	v_fmac_f32_e32 v178, v45, v69
	v_fmac_f32_e32 v68, v55, v69
	s_waitcnt lgkmcnt(0)
	v_mul_f32_e32 v179, v40, v78
	v_mul_f32_e32 v69, v58, v78
	v_fmac_f32_e32 v182, v43, v75
	v_fmac_f32_e32 v72, v51, v75
	v_fmac_f32_e32 v178, v38, v70
	v_fmac_f32_e32 v68, v52, v70
	v_fmac_f32_e32 v179, v41, v79
	v_fmac_f32_e32 v69, v59, v79
	v_add_f32_e32 v182, 0, v182
	v_add_f32_e32 v72, 0, v72
	v_fmac_f32_e32 v178, v39, v71
	v_fmac_f32_e32 v68, v53, v71
	v_fmac_f32_e32 v179, v34, v80
	v_fmac_f32_e32 v69, v56, v80
	v_mul_f32_e32 v174, v36, v64
	v_mul_f32_e32 v64, v62, v64
	v_add_f32_e32 v178, v178, v182
	v_add_f32_e32 v68, v68, v72
	v_fmac_f32_e32 v179, v35, v81
	v_fmac_f32_e32 v69, v57, v81
	v_fmac_f32_e32 v174, v37, v65
	v_fmac_f32_e32 v64, v63, v65
	v_add_f32_e32 v186, v179, v178
	v_add_f32_e32 v76, v69, v68
	v_fmac_f32_e32 v174, v32, v66
	v_fmac_f32_e32 v64, v60, v66
	ds_read_b128 v[68:71], v8 offset:29696
	ds_read_b128 v[72:75], v8 offset:28672
	v_fmac_f32_e32 v174, v33, v67
	v_fmac_f32_e32 v64, v61, v67
	v_add_f32_e32 v186, v174, v186
	v_add_f32_e32 v76, v64, v76
	ds_read_b128 v[64:67], v8 offset:31744
	ds_read_b128 v[78:81], v8 offset:30720
	s_waitcnt lgkmcnt(3)
	v_mul_f32_e32 v178, v44, v68
	v_mul_f32_e32 v68, v54, v68
	s_waitcnt lgkmcnt(2)
	v_mul_f32_e32 v182, v46, v72
	v_mul_f32_e32 v72, v48, v72
	v_fmac_f32_e32 v182, v47, v73
	v_fmac_f32_e32 v72, v49, v73
	v_fmac_f32_e32 v182, v42, v74
	v_fmac_f32_e32 v72, v50, v74
	v_fmac_f32_e32 v178, v45, v69
	v_fmac_f32_e32 v68, v55, v69
	s_waitcnt lgkmcnt(0)
; DI void phase7(const Params& p, char* smem) {
;     ...
; #pragma unroll
;     for (int e = 0; e < 16; ++e) {
;       float s = 0.f;
; #pragma unroll
;       for (int i = 0; i < 4; ++i) { const float4 wv = *(const float4*)(wr + e * DM + lane * 4 + 256 * i); s += v[i].x * wv.x + v[i].y * wv.y + v[i].z * wv.z + v[i].w * wv.w; }
;       a[e] = s;
;       if ((e & 3) == 3) __builtin_amdgcn_sched_barrier(0);
;     }
	v_mul_f32_e32 v179, v40, v78
	v_mul_f32_e32 v69, v58, v78
	v_fmac_f32_e32 v182, v43, v75
	v_fmac_f32_e32 v72, v51, v75
	v_fmac_f32_e32 v178, v38, v70
	v_fmac_f32_e32 v68, v52, v70
	v_fmac_f32_e32 v179, v41, v79
	v_fmac_f32_e32 v69, v59, v79
	v_mul_f32_e32 v174, v36, v64
	v_mul_f32_e32 v64, v62, v64
	v_add_f32_e32 v182, 0, v182
	v_add_f32_e32 v72, 0, v72
	v_fmac_f32_e32 v178, v39, v71
	v_fmac_f32_e32 v68, v53, v71
	v_fmac_f32_e32 v179, v34, v80
	v_fmac_f32_e32 v69, v56, v80
	v_fmac_f32_e32 v174, v37, v65
	v_fmac_f32_e32 v64, v63, v65
	v_add_f32_e32 v178, v178, v182
	v_add_f32_e32 v68, v68, v72
	v_fmac_f32_e32 v179, v35, v81
	v_fmac_f32_e32 v69, v57, v81
	v_fmac_f32_e32 v174, v32, v66
	v_fmac_f32_e32 v64, v60, v66
	v_add_f32_e32 v178, v179, v178
	v_add_f32_e32 v68, v69, v68
	v_fmac_f32_e32 v174, v33, v67
	v_fmac_f32_e32 v64, v61, v67
	v_add_f32_e32 v192, v174, v178
	v_add_f32_e32 v82, v64, v68
	ds_read_b128 v[64:67], v8 offset:32768
	ds_read_b128 v[68:71], v8 offset:33792
	ds_read_b128 v[72:75], v8 offset:34816
	s_waitcnt lgkmcnt(2)
	v_mul_f32_e32 v175, v47, v65
	v_mul_f32_e32 v65, v49, v65
	s_waitcnt lgkmcnt(1)
	v_mul_f32_e32 v179, v45, v69
	v_mul_f32_e32 v69, v55, v69
	v_fmac_f32_e32 v175, v46, v64
	v_fmac_f32_e32 v65, v48, v64
	v_fmac_f32_e32 v179, v44, v68
	v_fmac_f32_e32 v69, v54, v68
	v_fmac_f32_e32 v175, v42, v66
	v_fmac_f32_e32 v65, v50, v66
	v_fmac_f32_e32 v175, v43, v67
	v_fmac_f32_e32 v65, v51, v67
	v_fmac_f32_e32 v179, v38, v70
	v_fmac_f32_e32 v69, v52, v70
	v_add_f32_e32 v174, 0, v175
	v_add_f32_e32 v64, 0, v65
	v_fmac_f32_e32 v179, v39, v71
	v_fmac_f32_e32 v69, v53, v71
	v_add_f32_e32 v178, v174, v179
	v_add_f32_e32 v68, v64, v69
	ds_read_b128 v[64:67], v8 offset:35840
	s_waitcnt lgkmcnt(1)
	v_mul_f32_e32 v179, v41, v73
	v_mul_f32_e32 v69, v59, v73
	v_fmac_f32_e32 v179, v40, v72
	v_fmac_f32_e32 v69, v58, v72
	v_fmac_f32_e32 v179, v34, v74
	v_fmac_f32_e32 v69, v56, v74
	v_fmac_f32_e32 v179, v35, v75
	v_fmac_f32_e32 v69, v57, v75
	s_waitcnt lgkmcnt(0)
	v_mul_f32_e32 v175, v37, v65
	v_mul_f32_e32 v65, v63, v65
	v_fmac_f32_e32 v175, v36, v64
	v_fmac_f32_e32 v65, v62, v64
	v_add_f32_e32 v188, v178, v179
	v_add_f32_e32 v78, v68, v69
	v_fmac_f32_e32 v175, v32, v66
	v_fmac_f32_e32 v65, v60, v66
	ds_read_b128 v[68:71], v8 offset:37888
	ds_read_b128 v[72:75], v8 offset:36864
	v_fmac_f32_e32 v175, v33, v67
	v_fmac_f32_e32 v65, v61, v67
	v_add_f32_e32 v193, v188, v175
	v_add_f32_e32 v83, v78, v65
	ds_read_b128 v[64:67], v8 offset:39936
	ds_read_b128 v[78:81], v8 offset:38912
	s_waitcnt lgkmcnt(3)
	v_mul_f32_e32 v178, v44, v68
	v_mul_f32_e32 v68, v54, v68
	s_waitcnt lgkmcnt(2)
	v_mul_f32_e32 v182, v46, v72
	v_mul_f32_e32 v72, v48, v72
	v_fmac_f32_e32 v182, v47, v73
	v_fmac_f32_e32 v72, v49, v73
	v_fmac_f32_e32 v182, v42, v74
	v_fmac_f32_e32 v72, v50, v74
	v_fmac_f32_e32 v178, v45, v69
	v_fmac_f32_e32 v68, v55, v69
	s_waitcnt lgkmcnt(0)
	v_mul_f32_e32 v179, v40, v78
	v_mul_f32_e32 v69, v58, v78
	v_fmac_f32_e32 v182, v43, v75
	v_fmac_f32_e32 v72, v51, v75
	v_fmac_f32_e32 v178, v38, v70
	v_fmac_f32_e32 v68, v52, v70
	v_fmac_f32_e32 v179, v41, v79
	v_fmac_f32_e32 v69, v59, v79
	v_add_f32_e32 v182, 0, v182
	v_add_f32_e32 v72, 0, v72
	v_fmac_f32_e32 v178, v39, v71
	v_fmac_f32_e32 v68, v53, v71
	v_fmac_f32_e32 v179, v34, v80
	v_fmac_f32_e32 v69, v56, v80
	v_mul_f32_e32 v174, v36, v64
	v_mul_f32_e32 v64, v62, v64
	v_add_f32_e32 v178, v178, v182
	v_add_f32_e32 v68, v68, v72
	v_fmac_f32_e32 v179, v35, v81
	v_fmac_f32_e32 v69, v57, v81
	v_fmac_f32_e32 v174, v37, v65
	v_fmac_f32_e32 v64, v63, v65
	v_add_f32_e32 v188, v179, v178
	v_add_f32_e32 v78, v69, v68
	v_fmac_f32_e32 v174, v32, v66
	v_fmac_f32_e32 v64, v60, v66
	ds_read_b128 v[68:71], v8 offset:41984
	ds_read_b128 v[72:75], v8 offset:40960
	v_fmac_f32_e32 v174, v33, v67
	v_fmac_f32_e32 v64, v61, v67
	v_add_f32_e32 v196, v174, v188
	v_add_f32_e32 v86, v64, v78
	ds_read_b128 v[64:67], v8 offset:44032
	ds_read_b128 v[78:81], v8 offset:43008
	s_waitcnt lgkmcnt(3)
	v_mul_f32_e32 v178, v44, v68
	v_mul_f32_e32 v68, v54, v68
	s_waitcnt lgkmcnt(2)
	v_mul_f32_e32 v182, v46, v72
	v_mul_f32_e32 v72, v48, v72
	v_fmac_f32_e32 v182, v47, v73
	v_fmac_f32_e32 v72, v49, v73
	v_fmac_f32_e32 v182, v42, v74
	v_fmac_f32_e32 v72, v50, v74
	v_fmac_f32_e32 v178, v45, v69
	v_fmac_f32_e32 v68, v55, v69
	s_waitcnt lgkmcnt(0)
	v_mul_f32_e32 v179, v40, v78
	v_mul_f32_e32 v69, v58, v78
	v_fmac_f32_e32 v182, v43, v75
	v_fmac_f32_e32 v72, v51, v75
	v_fmac_f32_e32 v178, v38, v70
	v_fmac_f32_e32 v68, v52, v70
	v_fmac_f32_e32 v179, v41, v79
	v_fmac_f32_e32 v69, v59, v79
	v_add_f32_e32 v182, 0, v182
	v_add_f32_e32 v72, 0, v72
	v_fmac_f32_e32 v178, v39, v71
	v_fmac_f32_e32 v68, v53, v71
	v_fmac_f32_e32 v179, v34, v80
	v_fmac_f32_e32 v69, v56, v80
	v_mul_f32_e32 v174, v36, v64
	v_mul_f32_e32 v64, v62, v64
	v_add_f32_e32 v178, v178, v182
	v_add_f32_e32 v68, v68, v72
	v_fmac_f32_e32 v179, v35, v81
	v_fmac_f32_e32 v69, v57, v81
	v_fmac_f32_e32 v174, v37, v65
	v_fmac_f32_e32 v64, v63, v65
	v_add_f32_e32 v188, v179, v178
	v_add_f32_e32 v78, v69, v68
	v_fmac_f32_e32 v174, v32, v66
	v_fmac_f32_e32 v64, v60, v66
	ds_read_b128 v[68:71], v8 offset:46080
	ds_read_b128 v[72:75], v8 offset:45056
	v_fmac_f32_e32 v174, v33, v67
	v_fmac_f32_e32 v64, v61, v67
	v_add_f32_e32 v197, v174, v188
	v_add_f32_e32 v87, v64, v78
	ds_read_b128 v[64:67], v8 offset:48128
	ds_read_b128 v[78:81], v8 offset:47104
	s_waitcnt lgkmcnt(3)
	v_mul_f32_e32 v178, v44, v68
	v_mul_f32_e32 v68, v54, v68
	s_waitcnt lgkmcnt(2)
	v_mul_f32_e32 v182, v46, v72
	v_mul_f32_e32 v72, v48, v72
	v_fmac_f32_e32 v182, v47, v73
	v_fmac_f32_e32 v72, v49, v73
	v_fmac_f32_e32 v182, v42, v74
	v_fmac_f32_e32 v72, v50, v74
	v_fmac_f32_e32 v178, v45, v69
	v_fmac_f32_e32 v68, v55, v69
	s_waitcnt lgkmcnt(0)
; DI void phase7(const Params& p, char* smem) {
;     ...
; #pragma unroll
;     for (int e = 0; e < 16; ++e) {
;       float s = 0.f;
; #pragma unroll
;       for (int i = 0; i < 4; ++i) { const float4 wv = *(const float4*)(wr + e * DM + lane * 4 + 256 * i); s += v[i].x * wv.x + v[i].y * wv.y + v[i].z * wv.z + v[i].w * wv.w; }
;       a[e] = s;
;       if ((e & 3) == 3) __builtin_amdgcn_sched_barrier(0);
;     }
	v_mul_f32_e32 v179, v40, v78
	v_mul_f32_e32 v69, v58, v78
	v_fmac_f32_e32 v182, v43, v75
	v_fmac_f32_e32 v72, v51, v75
	v_fmac_f32_e32 v178, v38, v70
	v_fmac_f32_e32 v68, v52, v70
	v_fmac_f32_e32 v179, v41, v79
	v_fmac_f32_e32 v69, v59, v79
	v_mul_f32_e32 v174, v36, v64
	v_mul_f32_e32 v64, v62, v64
	v_add_f32_e32 v182, 0, v182
	v_add_f32_e32 v72, 0, v72
	v_fmac_f32_e32 v178, v39, v71
	v_fmac_f32_e32 v68, v53, v71
	v_fmac_f32_e32 v179, v34, v80
	v_fmac_f32_e32 v69, v56, v80
	v_fmac_f32_e32 v174, v37, v65
	v_fmac_f32_e32 v64, v63, v65
	v_add_f32_e32 v178, v178, v182
	v_add_f32_e32 v68, v68, v72
	v_fmac_f32_e32 v179, v35, v81
	v_fmac_f32_e32 v69, v57, v81
	v_fmac_f32_e32 v174, v32, v66
	v_fmac_f32_e32 v64, v60, v66
	v_add_f32_e32 v178, v179, v178
	v_add_f32_e32 v68, v69, v68
	v_fmac_f32_e32 v174, v33, v67
	v_fmac_f32_e32 v64, v61, v67
	v_add_f32_e32 v198, v174, v178
	v_add_f32_e32 v88, v64, v68
	ds_read_b128 v[64:67], v8 offset:49152
	ds_read_b128 v[68:71], v8 offset:50176
	ds_read_b128 v[72:75], v8 offset:51200
	s_waitcnt lgkmcnt(2)
	v_mul_f32_e32 v175, v47, v65
	v_mul_f32_e32 v65, v49, v65
	s_waitcnt lgkmcnt(1)
	v_mul_f32_e32 v179, v45, v69
	v_mul_f32_e32 v69, v55, v69
	v_fmac_f32_e32 v175, v46, v64
	v_fmac_f32_e32 v65, v48, v64
	v_fmac_f32_e32 v179, v44, v68
	v_fmac_f32_e32 v69, v54, v68
	v_fmac_f32_e32 v175, v42, v66
	v_fmac_f32_e32 v65, v50, v66
	v_fmac_f32_e32 v175, v43, v67
	v_fmac_f32_e32 v65, v51, v67
	v_fmac_f32_e32 v179, v38, v70
	v_fmac_f32_e32 v69, v52, v70
	v_add_f32_e32 v174, 0, v175
	v_add_f32_e32 v64, 0, v65
	v_fmac_f32_e32 v179, v39, v71
	v_fmac_f32_e32 v69, v53, v71
	v_add_f32_e32 v178, v174, v179
	v_add_f32_e32 v68, v64, v69
	ds_read_b128 v[64:67], v8 offset:52224
	s_waitcnt lgkmcnt(1)
	v_mul_f32_e32 v179, v41, v73
	v_mul_f32_e32 v69, v59, v73
	v_fmac_f32_e32 v179, v40, v72
	v_fmac_f32_e32 v69, v58, v72
	v_fmac_f32_e32 v179, v34, v74
	v_fmac_f32_e32 v69, v56, v74
	v_fmac_f32_e32 v179, v35, v75
	v_fmac_f32_e32 v69, v57, v75
	s_waitcnt lgkmcnt(0)
	v_mul_f32_e32 v175, v37, v65
	v_mul_f32_e32 v65, v63, v65
	v_fmac_f32_e32 v175, v36, v64
	v_fmac_f32_e32 v65, v62, v64
	v_add_f32_e32 v188, v178, v179
	v_add_f32_e32 v78, v68, v69
	v_fmac_f32_e32 v175, v32, v66
	v_fmac_f32_e32 v65, v60, v66
	ds_read_b128 v[68:71], v8 offset:54272
	ds_read_b128 v[72:75], v8 offset:53248
	v_fmac_f32_e32 v175, v33, v67
	v_fmac_f32_e32 v65, v61, v67
	v_add_f32_e32 v199, v188, v175
	v_add_f32_e32 v89, v78, v65
	ds_read_b128 v[64:67], v8 offset:56320
	ds_read_b128 v[78:81], v8 offset:55296
	s_waitcnt lgkmcnt(3)
	v_mul_f32_e32 v178, v44, v68
	v_mul_f32_e32 v68, v54, v68
	s_waitcnt lgkmcnt(2)
	v_mul_f32_e32 v182, v46, v72
	v_mul_f32_e32 v72, v48, v72
	v_fmac_f32_e32 v182, v47, v73
	v_fmac_f32_e32 v72, v49, v73
	v_fmac_f32_e32 v182, v42, v74
	v_fmac_f32_e32 v72, v50, v74
	v_fmac_f32_e32 v178, v45, v69
	v_fmac_f32_e32 v68, v55, v69
	s_waitcnt lgkmcnt(0)
	v_mul_f32_e32 v179, v40, v78
	v_mul_f32_e32 v69, v58, v78
	v_fmac_f32_e32 v182, v43, v75
	v_fmac_f32_e32 v72, v51, v75
	v_fmac_f32_e32 v178, v38, v70
	v_fmac_f32_e32 v68, v52, v70
	v_fmac_f32_e32 v179, v41, v79
	v_fmac_f32_e32 v69, v59, v79
	v_add_f32_e32 v182, 0, v182
	v_add_f32_e32 v72, 0, v72
	v_fmac_f32_e32 v178, v39, v71
	v_fmac_f32_e32 v68, v53, v71
	v_fmac_f32_e32 v179, v34, v80
	v_fmac_f32_e32 v69, v56, v80
	v_mul_f32_e32 v174, v36, v64
	v_mul_f32_e32 v64, v62, v64
	v_add_f32_e32 v178, v178, v182
	v_add_f32_e32 v68, v68, v72
	v_fmac_f32_e32 v179, v35, v81
	v_fmac_f32_e32 v69, v57, v81
	v_fmac_f32_e32 v174, v37, v65
	v_fmac_f32_e32 v64, v63, v65
	v_add_f32_e32 v188, v179, v178
	v_add_f32_e32 v78, v69, v68
	v_fmac_f32_e32 v174, v32, v66
	v_fmac_f32_e32 v64, v60, v66
	ds_read_b128 v[68:71], v8 offset:58368
	ds_read_b128 v[72:75], v8 offset:57344
	v_fmac_f32_e32 v174, v33, v67
	v_fmac_f32_e32 v64, v61, v67
	v_add_f32_e32 v200, v174, v188
	v_add_f32_e32 v90, v64, v78
	ds_read_b128 v[64:67], v8 offset:60416
	ds_read_b128 v[78:81], v8 offset:59392
	s_waitcnt lgkmcnt(3)
	v_mul_f32_e32 v178, v44, v68
	v_mul_f32_e32 v68, v54, v68
	s_waitcnt lgkmcnt(2)
	v_mul_f32_e32 v182, v46, v72
	v_mul_f32_e32 v72, v48, v72
	v_fmac_f32_e32 v182, v47, v73
	v_fmac_f32_e32 v72, v49, v73
	v_fmac_f32_e32 v182, v42, v74
	v_fmac_f32_e32 v72, v50, v74
	v_fmac_f32_e32 v178, v45, v69
	v_fmac_f32_e32 v68, v55, v69
	s_waitcnt lgkmcnt(0)
	v_mul_f32_e32 v179, v40, v78
	v_mul_f32_e32 v69, v58, v78
	v_fmac_f32_e32 v182, v43, v75
	v_fmac_f32_e32 v72, v51, v75
	v_fmac_f32_e32 v178, v38, v70
	v_fmac_f32_e32 v68, v52, v70
	v_fmac_f32_e32 v179, v41, v79
	v_fmac_f32_e32 v69, v59, v79
	v_add_f32_e32 v182, 0, v182
	v_add_f32_e32 v72, 0, v72
	v_fmac_f32_e32 v178, v39, v71
	v_fmac_f32_e32 v68, v53, v71
	v_fmac_f32_e32 v179, v34, v80
	v_fmac_f32_e32 v69, v56, v80
	v_add_f32_e32 v178, v178, v182
	v_add_f32_e32 v68, v68, v72
	v_fmac_f32_e32 v179, v35, v81
	v_fmac_f32_e32 v69, v57, v81
	v_add_f32_e32 v188, v179, v178
	v_add_f32_e32 v78, v69, v68
	ds_read_b128 v[68:71], v8 offset:62464
	ds_read_b128 v[72:75], v8 offset:61440
	v_mul_f32_e32 v174, v36, v64
	v_mul_f32_e32 v64, v62, v64
	v_fmac_f32_e32 v174, v37, v65
	v_fmac_f32_e32 v64, v63, v65
	v_fmac_f32_e32 v174, v32, v66
	v_fmac_f32_e32 v64, v60, v66
	v_fmac_f32_e32 v174, v33, v67
	v_fmac_f32_e32 v64, v61, v67
	v_add_f32_e32 v201, v174, v188
	v_add_f32_e32 v91, v64, v78
	ds_read_b128 v[64:67], v8 offset:64512
	ds_read_b128 v[78:81], v8 offset:63488
	s_waitcnt lgkmcnt(2)
; DI void phase7(const Params& p, char* smem) {
;     ...
; #pragma unroll
;     for (int e = 0; e < 16; ++e) {
;       float s = 0.f;
; #pragma unroll
;       for (int i = 0; i < 4; ++i) { const float4 wv = *(const float4*)(wr + e * DM + lane * 4 + 256 * i); s += v[i].x * wv.x + v[i].y * wv.y + v[i].z * wv.z + v[i].w * wv.w; }
;       a[e] = s;
;       if ((e & 3) == 3) __builtin_amdgcn_sched_barrier(0);
;     }
;     float a8[8], a4[4], a2[2], a1;
;     {
;       const bool up = lane & 32;
; #pragma unroll
;       for (int j = 0; j < 8; ++j) { const float send = up ? a[j] : a[j + 8]; const float keep = up ? a[j + 8] : a[j]; a8[j] = keep + __shfl_xor(send, 32); }
;     }
;     {
;       const bool up = lane & 16;
; #pragma unroll
;       for (int j = 0; j < 4; ++j) { const float send = up ? a8[j] : a8[j + 4]; const float keep = up ? a8[j + 4] : a8[j]; a4[j] = keep + __shfl_xor(send, 16); }
;     }
	v_mul_f32_e32 v158, v46, v72
	v_mul_f32_e32 v48, v48, v72
	v_fmac_f32_e32 v158, v47, v73
	v_fmac_f32_e32 v48, v49, v73
	v_mul_f32_e32 v159, v44, v68
	v_mul_f32_e32 v49, v54, v68
	v_fmac_f32_e32 v158, v42, v74
	v_fmac_f32_e32 v48, v50, v74
	v_fmac_f32_e32 v159, v45, v69
	v_fmac_f32_e32 v49, v55, v69
	v_fmac_f32_e32 v158, v43, v75
	v_fmac_f32_e32 v48, v51, v75
	v_fmac_f32_e32 v159, v38, v70
	v_fmac_f32_e32 v49, v52, v70
	v_add_f32_e32 v158, 0, v158
	v_add_f32_e32 v48, 0, v48
	v_fmac_f32_e32 v159, v39, v71
	v_fmac_f32_e32 v49, v53, v71
	v_add_f32_e32 v158, v159, v158
	v_add_f32_e32 v48, v49, v48
	s_waitcnt lgkmcnt(0)
	v_mul_f32_e32 v159, v40, v78
	v_mul_f32_e32 v49, v58, v78
	v_fmac_f32_e32 v159, v41, v79
	v_fmac_f32_e32 v49, v59, v79
	v_fmac_f32_e32 v159, v34, v80
	v_fmac_f32_e32 v49, v56, v80
	v_fmac_f32_e32 v159, v35, v81
	v_fmac_f32_e32 v49, v57, v81
	v_add_f32_e32 v158, v159, v158
	v_add_f32_e32 v48, v49, v48
	v_mul_f32_e32 v159, v36, v64
	v_mul_f32_e32 v49, v62, v64
	v_fmac_f32_e32 v159, v37, v65
	v_fmac_f32_e32 v49, v63, v65
	v_fmac_f32_e32 v159, v32, v66
	v_fmac_f32_e32 v49, v60, v66
	v_fmac_f32_e32 v159, v33, v67
	v_fmac_f32_e32 v49, v61, v67
	v_add_f32_e32 v158, v159, v158
	v_add_f32_e32 v48, v49, v48
	v_cndmask_b32_e64 v159, v110, v193, s[4:5]
	v_cndmask_b32_e64 v49, v0, v83, s[4:5]
	v_cndmask_b32_e64 v161, v112, v197, s[4:5]
	v_cndmask_b32_e64 v51, v2, v87, s[4:5]
	ds_bpermute_b32 v159, v11, v159
	ds_bpermute_b32 v49, v11, v49
	ds_bpermute_b32 v161, v11, v161
	ds_bpermute_b32 v51, v11, v51
	v_cndmask_b32_e64 v110, v193, v110, s[4:5]
	v_cndmask_b32_e64 v0, v83, v0, s[4:5]
	v_cndmask_b32_e64 v160, v111, v196, s[4:5]
	v_cndmask_b32_e64 v50, v1, v86, s[4:5]
	v_cndmask_b32_e64 v112, v197, v112, s[4:5]
	v_cndmask_b32_e64 v2, v87, v2, s[4:5]
	ds_bpermute_b32 v160, v11, v160
	ds_bpermute_b32 v50, v11, v50
	s_waitcnt lgkmcnt(2)
	v_add_f32_e32 v110, v110, v159
	v_add_f32_e32 v0, v0, v49
	s_waitcnt lgkmcnt(1)
	v_add_f32_e32 v112, v112, v161
	v_add_f32_e32 v2, v2, v51
	v_cndmask_b32_e64 v159, v113, v198, s[4:5]
	v_cndmask_b32_e64 v49, v3, v88, s[4:5]
	v_cndmask_b32_e64 v161, v119, v200, s[4:5]
	v_cndmask_b32_e64 v51, v9, v90, s[4:5]
	ds_bpermute_b32 v159, v11, v159
	ds_bpermute_b32 v49, v11, v49
	ds_bpermute_b32 v161, v11, v161
	ds_bpermute_b32 v51, v11, v51
	v_cndmask_b32_e64 v111, v196, v111, s[4:5]
	v_cndmask_b32_e64 v1, v86, v1, s[4:5]
	s_waitcnt lgkmcnt(2)
	v_add_f32_e32 v111, v111, v160
	v_add_f32_e32 v1, v1, v50
	v_cndmask_b32_e64 v113, v198, v113, s[4:5]
	v_cndmask_b32_e64 v3, v88, v3, s[4:5]
	v_cndmask_b32_e64 v160, v116, v199, s[4:5]
	v_cndmask_b32_e64 v50, v6, v89, s[4:5]
	v_cndmask_b32_e64 v119, v200, v119, s[4:5]
	v_cndmask_b32_e64 v9, v90, v9, s[4:5]
	ds_bpermute_b32 v160, v11, v160
	ds_bpermute_b32 v50, v11, v50
	s_waitcnt lgkmcnt(2)
	v_add_f32_e32 v113, v113, v159
	v_add_f32_e32 v3, v3, v49
	s_waitcnt lgkmcnt(1)
	v_add_f32_e32 v119, v119, v161
	v_add_f32_e32 v9, v9, v51
	v_cndmask_b32_e64 v159, v186, v201, s[4:5]
	v_cndmask_b32_e64 v49, v76, v91, s[4:5]
	v_cndmask_b32_e64 v161, v192, v158, s[4:5]
	v_cndmask_b32_e64 v51, v82, v48, s[4:5]
	ds_bpermute_b32 v159, v11, v159
	ds_bpermute_b32 v49, v11, v49
	ds_bpermute_b32 v161, v11, v161
	ds_bpermute_b32 v51, v11, v51
	v_cndmask_b32_e64 v116, v199, v116, s[4:5]
	v_cndmask_b32_e64 v6, v89, v6, s[4:5]
	s_waitcnt lgkmcnt(2)
	v_add_f32_e32 v116, v116, v160
	v_add_f32_e32 v6, v6, v50
	v_cndmask_b32_e64 v160, v201, v186, s[4:5]
	v_cndmask_b32_e64 v50, v91, v76, s[4:5]
	v_cndmask_b32_e64 v158, v158, v192, s[4:5]
	v_cndmask_b32_e64 v48, v48, v82, s[4:5]
	s_waitcnt lgkmcnt(1)
	v_add_f32_e32 v159, v160, v159
	v_add_f32_e32 v49, v50, v49
	s_waitcnt lgkmcnt(0)
	v_add_f32_e32 v158, v158, v161
	v_add_f32_e32 v48, v48, v51
	v_cndmask_b32_e64 v162, v110, v116, s[6:7]
	v_cndmask_b32_e64 v52, v0, v6, s[6:7]
	v_cndmask_b32_e64 v110, v116, v110, s[6:7]
	v_cndmask_b32_e64 v0, v6, v0, s[6:7]
	v_cndmask_b32_e64 v116, v111, v119, s[6:7]
	v_cndmask_b32_e64 v6, v1, v9, s[6:7]
	v_cndmask_b32_e64 v111, v119, v111, s[6:7]
	v_cndmask_b32_e64 v1, v9, v1, s[6:7]
	v_cndmask_b32_e64 v119, v112, v159, s[6:7]
	v_cndmask_b32_e64 v9, v2, v49, s[6:7]
	v_cndmask_b32_e64 v160, v113, v158, s[6:7]
	v_cndmask_b32_e64 v50, v3, v48, s[6:7]
	ds_bpermute_b32 v162, v13, v162
	ds_bpermute_b32 v52, v13, v52
	ds_bpermute_b32 v116, v13, v116
	ds_bpermute_b32 v6, v13, v6
	ds_bpermute_b32 v119, v13, v119
	ds_bpermute_b32 v9, v13, v9
	ds_bpermute_b32 v160, v13, v160
	ds_bpermute_b32 v50, v13, v50
	v_cndmask_b32_e64 v112, v159, v112, s[6:7]
	v_cndmask_b32_e64 v2, v49, v2, s[6:7]
	v_cndmask_b32_e64 v113, v158, v113, s[6:7]
	v_cndmask_b32_e64 v3, v48, v3, s[6:7]
	s_waitcnt lgkmcnt(3)
; DI void phase7(const Params& p, char* smem) {
;     ...
;     {
;       const bool up = lane & 8;
; #pragma unroll
;       for (int j = 0; j < 2; ++j) { const float send = up ? a4[j] : a4[j + 2]; const float keep = up ? a4[j + 2] : a4[j]; a2[j] = keep + __shfl_xor(send, 8); }
;     }
;     {
;       const bool up = lane & 4;
;       const float send = up ? a2[0] : a2[1]; const float keep = up ? a2[1] : a2[0]; a1 = keep + __shfl_xor(send, 4);
;     }
;     a1 += __shfl_xor(a1, 2);
;     a1 += __shfl_xor(a1, 1);
;     float mx = a1;
; #pragma unroll
;     for (int o = 4; o <= 32; o <<= 1) mx = fmaxf(mx, __shfl_xor(mx, o));
;     const float ex = __expf(a1 - mx);
;     float sm = ex;
; #pragma unroll
;     for (int o = 4; o <= 32; o <<= 1) sm += __shfl_xor(sm, o);
;     if ((lane & 3) == 0) {
;       const int e = (lane >> 2) & 15;
;       p.aff[((size_t)((R >> 11) * NE + e)) * SEQ + (R & 2047)] = ex / sm;
;     }
	v_add_f32_e32 v110, v110, v162
	v_add_f32_e32 v0, v0, v52
	s_waitcnt lgkmcnt(2)
	v_add_f32_e32 v111, v111, v116
	v_add_f32_e32 v1, v1, v6
	s_waitcnt lgkmcnt(1)
	v_add_f32_e32 v112, v112, v119
	v_add_f32_e32 v2, v2, v9
	s_waitcnt lgkmcnt(0)
	v_add_f32_e32 v113, v113, v160
	v_add_f32_e32 v3, v3, v50
	v_cndmask_b32_e64 v116, v110, v112, s[8:9]
	v_cndmask_b32_e64 v6, v0, v2, s[8:9]
	v_cndmask_b32_e64 v119, v111, v113, s[8:9]
	v_cndmask_b32_e64 v9, v1, v3, s[8:9]
	ds_bpermute_b32 v116, v15, v116
	ds_bpermute_b32 v6, v15, v6
	ds_bpermute_b32 v119, v15, v119
	ds_bpermute_b32 v9, v15, v9
	v_cndmask_b32_e64 v110, v112, v110, s[8:9]
	v_cndmask_b32_e64 v0, v2, v0, s[8:9]
	v_cndmask_b32_e64 v111, v113, v111, s[8:9]
	v_cndmask_b32_e64 v1, v3, v1, s[8:9]
	s_waitcnt lgkmcnt(1)
	v_add_f32_e32 v110, v110, v116
	v_add_f32_e32 v0, v0, v6
	s_waitcnt lgkmcnt(0)
	v_add_f32_e32 v111, v111, v119
	v_add_f32_e32 v1, v1, v9
	v_cndmask_b32_e64 v112, v110, v111, s[10:11]
	v_cndmask_b32_e64 v2, v0, v1, s[10:11]
	ds_bpermute_b32 v112, v31, v112
	ds_bpermute_b32 v2, v31, v2
	v_cndmask_b32_e64 v110, v111, v110, s[10:11]
	v_cndmask_b32_e64 v0, v1, v0, s[10:11]
	s_waitcnt lgkmcnt(0)
	v_add_f32_e32 v110, v110, v112
	v_add_f32_e32 v0, v0, v2
	ds_bpermute_b32 v111, v77, v110
	ds_bpermute_b32 v1, v77, v0
	s_waitcnt lgkmcnt(0)
	v_add_f32_e32 v110, v110, v111
	v_add_f32_e32 v0, v0, v1
	ds_bpermute_b32 v111, v84, v110
	ds_bpermute_b32 v1, v84, v0
	s_waitcnt lgkmcnt(0)
	v_add_f32_e32 v110, v110, v111
	v_add_f32_e32 v0, v0, v1
	ds_bpermute_b32 v111, v31, v110
	ds_bpermute_b32 v1, v31, v0
	s_waitcnt lgkmcnt(0)
	v_max_f32_e32 v111, v111, v111
	v_max_f32_e32 v1, v1, v1
	v_max_f32_e32 v111, v110, v111
	v_max_f32_e32 v1, v0, v1
	ds_bpermute_b32 v112, v15, v111
	ds_bpermute_b32 v2, v15, v1
	s_waitcnt lgkmcnt(0)
	v_max_f32_e32 v112, v112, v112
	v_max_f32_e32 v2, v2, v2
	v_max_f32_e32 v111, v111, v112
	v_max_f32_e32 v1, v1, v2
	ds_bpermute_b32 v112, v13, v111
	ds_bpermute_b32 v2, v13, v1
	s_waitcnt lgkmcnt(0)
	v_max_f32_e32 v112, v112, v112
	v_max_f32_e32 v2, v2, v2
	v_max_f32_e32 v111, v111, v112
	v_max_f32_e32 v1, v1, v2
	ds_bpermute_b32 v112, v11, v111
	ds_bpermute_b32 v2, v11, v1
	s_waitcnt lgkmcnt(0)
	v_max_f32_e32 v112, v112, v112
	v_max_f32_e32 v2, v2, v2
	v_max_f32_e32 v111, v111, v112
	v_max_f32_e32 v1, v1, v2
	v_sub_f32_e32 v110, v110, v111
	v_sub_f32_e32 v0, v0, v1
	v_mul_f32_e32 v110, 0x3fb8aa3b, v110
	v_mul_f32_e32 v0, 0x3fb8aa3b, v0
	v_exp_f32_e32 v110, v110
	v_exp_f32_e32 v0, v0
	ds_bpermute_b32 v111, v31, v110
	ds_bpermute_b32 v1, v31, v0
	s_waitcnt lgkmcnt(0)
	v_add_f32_e32 v111, v110, v111
	v_add_f32_e32 v1, v0, v1
	ds_bpermute_b32 v112, v15, v111
	ds_bpermute_b32 v2, v15, v1
	s_waitcnt lgkmcnt(0)
	v_add_f32_e32 v111, v111, v112
	v_add_f32_e32 v1, v1, v2
	ds_bpermute_b32 v112, v13, v111
	ds_bpermute_b32 v2, v13, v1
	s_waitcnt lgkmcnt(0)
	v_add_f32_e32 v111, v111, v112
	v_add_f32_e32 v1, v1, v2
	ds_bpermute_b32 v112, v11, v111
	ds_bpermute_b32 v2, v11, v1
	s_waitcnt vmcnt(0)
	s_and_saveexec_b64 s[16:17], s[12:13]
	s_xor_b64 s[16:17], exec, s[16:17]
	s_cbranch_execz .LBB0_965
	s_waitcnt lgkmcnt(0)
	v_add_f32_e32 v1, v1, v2
	v_div_scale_f32 v2, s[38:39], v1, v1, v0
	v_rcp_f32_e32 v3, v2
	v_div_scale_f32 v6, vcc, v0, v1, v0
	v_fma_f32 v9, -v2, v3, 1.0
	v_fmac_f32_e32 v3, v9, v3
	v_mul_f32_e32 v9, v6, v3
	v_fma_f32 v48, -v2, v9, v6
	v_fmac_f32_e32 v9, v48, v3
	v_fma_f32 v2, -v2, v9, v6
	v_div_fmas_f32 v2, v2, v3, v9
	v_div_fixup_f32 v2, v2, v1, v0
	v_ashrrev_i32_e32 v0, 7, v4
	v_and_or_b32 v0, v0, -16, v85
	v_ashrrev_i32_e32 v1, 31, v0
	v_and_b32_e32 v3, 0x7ff, v4
	v_lshlrev_b64 v[0:1], 13, v[0:1]
	v_lshl_add_u64 v[0:1], s[20:21], 0, v[0:1]
	v_lshlrev_b32_e32 v6, 2, v3
	v_lshl_add_u64 v[0:1], v[0:1], 0, v[6:7]
	global_store_dword v[0:1], v2, off
	s_and_b64 s[38:39], exec, s[14:15]
	s_cbranch_scc0 .LBB0_965
	v_mov_b32_e32 v0, v110
	v_mov_b32_e32 v1, v111
	v_mov_b32_e32 v2, v112
	s_waitcnt lgkmcnt(0)
	v_add_f32_e32 v1, v1, v2
	v_div_scale_f32 v2, s[38:39], v1, v1, v0
	v_rcp_f32_e32 v3, v2
	v_div_scale_f32 v6, vcc, v0, v1, v0
	v_fma_f32 v9, -v2, v3, 1.0
	v_fmac_f32_e32 v3, v9, v3
	v_mul_f32_e32 v9, v6, v3
	v_fma_f32 v48, -v2, v9, v6
	v_fmac_f32_e32 v9, v48, v3
	v_fma_f32 v2, -v2, v9, v6
	v_div_fmas_f32 v2, v2, v3, v9
	v_div_fixup_f32 v2, v2, v1, v0
	v_ashrrev_i32_e32 v0, 7, v5
	v_and_or_b32 v0, v0, -16, v85
	v_ashrrev_i32_e32 v1, 31, v0
	v_and_b32_e32 v3, 0x7ff, v5
	v_lshlrev_b64 v[0:1], 13, v[0:1]
	v_lshl_add_u64 v[0:1], s[20:21], 0, v[0:1]
	v_lshlrev_b32_e32 v6, 2, v3
	v_lshl_add_u64 v[0:1], v[0:1], 0, v[6:7]
	global_store_dword v[0:1], v2, off
